# candL (stagger) + PEER step-B memory block hoisted to body tops
# baseline (speedup 1.0000x reference)
; __device__ __forceinline__ f32x2 fp8x2_lo(unsigned w) { return __builtin_amdgcn_cvt_pk_f32_fp8(w, false); }
; __device__ __forceinline__ f32x2 fp8x2_hi(unsigned w) { return __builtin_amdgcn_cvt_pk_f32_fp8(w, true); }
; #define PB_IDS(T) do { const unsigned* kp_ = KP + (size_t)(T) * 256; _Pragma("unroll") for (int qq = 0; qq < 4; ++qq) idv[qq] = *(const u32x4*)(kp_ + 4 * qq); } while (0)
; template <bool NT>
; __device__ __forceinline__ void peer_passB(const Args& a, const PeerWork w) {
;     ...
;     int t = peer_tok(w, q), t1 = peer_tok(w, min(q + qs, ql));
;     PB_IDS(t);
;     PB_GATHER(t, vr, cf, hv);
;     PB_IDS(t1);
; #pragma unroll 1
;     for (;; q += qs) {
;         u32x4 vrn[16]; f32x4 cfn[4]; f32x2 hn;
;         PB_GATHER(t1, vrn, cfn, hn);
;         const int t2 = peer_tok(w, min(q + 2 * qs, ql));
;         PB_IDS(t2);
;         f32x2 acc[8];
; #pragma unroll
;         for (int m = 0; m < 8; ++m) acc[m] = (f32x2){0.f, 0.f};
; #pragma unroll
;         for (int k = 0; k < 16; ++k) {
;             const unsigned ww[4] = {vr[k].x, vr[k].y, vr[k].z, vr[k].w};
;             const float c = cf[k >> 2][k & 3]; const f32x2 c2 = {c, c};
; #pragma unroll
;             for (int wd = 0; wd < 4; ++wd) { acc[2 * wd] = __builtin_elementwise_fma(fp8x2_lo(ww[wd]), c2, acc[2 * wd]); acc[2 * wd + 1] = __builtin_elementwise_fma(fp8x2_hi(ww[wd]), c2, acc[2 * wd + 1]); }
.Lstag_b:
.LBB0_1587:
	s_waitcnt vmcnt(3)
	v_lshl_or_b32 v6, v6, 7, v1
	v_lshl_or_b32 v2, v2, 7, v1
	s_waitcnt vmcnt(1)
	v_lshl_or_b32 v14, v14, 7, v1
	v_lshl_or_b32 v10, v10, 7, v1
	global_load_dwordx4 v[106:109], v6, s[4:5]
	global_load_dwordx4 v[122:125], v2, s[4:5]
	v_lshl_or_b32 v6, v7, 7, v1
	v_lshl_or_b32 v2, v3, 7, v1
	s_mov_b32 s14, s6
	global_load_dwordx4 v[70:73], v14, s[4:5]
	global_load_dwordx4 v[86:89], v10, s[4:5]
	v_lshl_or_b32 v14, v15, 7, v1
	v_lshl_or_b32 v10, v11, 7, v1
	global_load_dwordx4 v[110:113], v6, s[4:5]
	global_load_dwordx4 v[126:129], v2, s[4:5]
	v_lshl_or_b32 v6, v8, 7, v1
	v_lshl_or_b32 v2, v4, 7, v1
	s_ashr_i32 s15, s6, 31
	global_load_dwordx4 v[74:77], v14, s[4:5]
	global_load_dwordx4 v[90:93], v10, s[4:5]
	v_lshl_or_b32 v14, v16, 7, v1
	v_lshl_or_b32 v10, v12, 7, v1
	global_load_dwordx4 v[114:117], v6, s[4:5]
	global_load_dwordx4 v[130:133], v2, s[4:5]
	v_lshl_or_b32 v6, v9, 7, v1
	v_lshl_or_b32 v2, v5, 7, v1
	s_lshl_b64 s[6:7], s[14:15], 9
	global_load_dwordx4 v[78:81], v14, s[4:5]
	global_load_dwordx4 v[98:101], v10, s[4:5]
	v_lshl_or_b32 v14, v17, 7, v1
	v_lshl_or_b32 v10, v13, 7, v1
	global_load_dwordx4 v[118:121], v6, s[4:5]
	global_load_dwordx4 v[134:137], v2, s[4:5]
	v_lshl_add_u64 v[2:3], v[184:185], 0, s[6:7]
	s_lshl_b64 s[6:7], s[14:15], 12
	global_load_dwordx4 v[82:85], v14, s[4:5]
	global_load_dwordx4 v[102:105], v10, s[4:5]
	global_load_dwordx4 v[142:145], v[2:3], off offset:48
	global_load_dwordx4 v[146:149], v[2:3], off offset:32
	global_load_dwordx4 v[150:153], v[2:3], off offset:16
	global_load_dwordx4 v[154:157], v[2:3], off
	v_lshl_add_u64 v[2:3], v[182:183], 0, s[6:7]
	s_add_i32 s6, s11, s18
	s_min_i32 s6, s6, 0x3fff
	s_ashr_i32 s7, s6, 31
	s_lshl_b64 s[28:29], s[6:7], 10
	v_lshl_add_u64 v[14:15], v[180:181], 0, s[28:29]
	global_load_dwordx2 v[188:189], v[2:3], off
	global_load_dwordx4 v[2:5], v[14:15], off offset:48
	global_load_dwordx4 v[6:9], v[14:15], off offset:32
	global_load_dwordx4 v[10:13], v[14:15], off offset:16
	global_load_dwordx4 v[14:17], v[14:15], off
	v_cvt_pk_f32_fp8_e32 v[192:193], v174
	v_cvt_pk_f32_fp8_e32 v[204:205], v170
	v_cvt_pk_f32_fp8_sdwa v[194:195], v174 src0_sel:WORD_1
	v_cvt_pk_f32_fp8_e32 v[196:197], v175
	v_pk_fma_f32 v[192:193], v[192:193], v[162:163], 0 op_sel_hi:[1,0,0]
	v_cvt_pk_f32_fp8_sdwa v[174:175], v175 src0_sel:WORD_1
	v_pk_fma_f32 v[192:193], v[204:205], v[162:163], v[192:193] op_sel:[0,1,0]
	v_cvt_pk_f32_fp8_sdwa v[204:205], v170 src0_sel:WORD_1
	v_pk_fma_f32 v[194:195], v[194:195], v[162:163], 0 op_sel_hi:[1,0,0]
	v_pk_fma_f32 v[174:175], v[174:175], v[162:163], 0 op_sel_hi:[1,0,0]
	v_cvt_pk_f32_fp8_e32 v[198:199], v176
	v_pk_fma_f32 v[194:195], v[204:205], v[162:163], v[194:195] op_sel:[0,1,0]
	v_cvt_pk_f32_fp8_e32 v[204:205], v171
	v_cvt_pk_f32_fp8_sdwa v[170:171], v171 src0_sel:WORD_1
	v_pk_fma_f32 v[198:199], v[198:199], v[162:163], 0 op_sel_hi:[1,0,0]
	v_cvt_pk_f32_fp8_sdwa v[200:201], v176 src0_sel:WORD_1
	v_cvt_pk_f32_fp8_e32 v[202:203], v177
	v_pk_fma_f32 v[170:171], v[170:171], v[162:163], v[174:175] op_sel:[0,1,0]
	v_cvt_pk_f32_fp8_e32 v[174:175], v172
	v_pk_fma_f32 v[200:201], v[200:201], v[162:163], 0 op_sel_hi:[1,0,0]
	v_cvt_pk_f32_fp8_sdwa v[176:177], v177 src0_sel:WORD_1
	v_pk_fma_f32 v[196:197], v[196:197], v[162:163], 0 op_sel_hi:[1,0,0]
	v_pk_fma_f32 v[174:175], v[174:175], v[162:163], v[198:199] op_sel:[0,1,0]
	v_cvt_pk_f32_fp8_sdwa v[198:199], v172 src0_sel:WORD_1
	v_pk_fma_f32 v[202:203], v[202:203], v[162:163], 0 op_sel_hi:[1,0,0]
	v_pk_fma_f32 v[176:177], v[176:177], v[162:163], 0 op_sel_hi:[1,0,0]
	v_pk_fma_f32 v[196:197], v[204:205], v[162:163], v[196:197] op_sel:[0,1,0]
	v_pk_fma_f32 v[198:199], v[198:199], v[162:163], v[200:201] op_sel:[0,1,0]
	v_cvt_pk_f32_fp8_e32 v[200:201], v173
	v_cvt_pk_f32_fp8_sdwa v[172:173], v173 src0_sel:WORD_1
	v_pk_fma_f32 v[200:201], v[200:201], v[162:163], v[202:203] op_sel:[0,1,0]
	v_pk_fma_f32 v[162:163], v[172:173], v[162:163], v[176:177] op_sel:[0,1,0]
	v_cvt_pk_f32_fp8_e32 v[172:173], v166
	v_cvt_pk_f32_fp8_sdwa v[176:177], v166 src0_sel:WORD_1
	v_pk_fma_f32 v[172:173], v[172:173], v[164:165], v[192:193] op_sel_hi:[1,0,1]
	v_cvt_pk_f32_fp8_e32 v[192:193], v167
	v_cvt_pk_f32_fp8_sdwa v[166:167], v167 src0_sel:WORD_1
	v_pk_fma_f32 v[176:177], v[176:177], v[164:165], v[194:195] op_sel_hi:[1,0,1]
	v_cvt_pk_f32_fp8_e32 v[194:195], v169
	v_pk_fma_f32 v[192:193], v[192:193], v[164:165], v[196:197] op_sel_hi:[1,0,1]
	v_pk_fma_f32 v[166:167], v[166:167], v[164:165], v[170:171] op_sel_hi:[1,0,1]
	v_cvt_pk_f32_fp8_e32 v[170:171], v168
	v_pk_fma_f32 v[194:195], v[194:195], v[164:165], v[200:201] op_sel_hi:[1,0,1]
	v_pk_fma_f32 v[170:171], v[170:171], v[164:165], v[174:175] op_sel_hi:[1,0,1]
	v_cvt_pk_f32_fp8_sdwa v[174:175], v168 src0_sel:WORD_1
	v_cvt_pk_f32_fp8_sdwa v[168:169], v169 src0_sel:WORD_1
	v_pk_fma_f32 v[174:175], v[174:175], v[164:165], v[198:199] op_sel_hi:[1,0,1]
	v_pk_fma_f32 v[162:163], v[168:169], v[164:165], v[162:163] op_sel_hi:[1,0,1]
	v_cvt_pk_f32_fp8_e32 v[168:169], v158
	v_mov_b32_e32 v164, v165
	v_pk_fma_f32 v[168:169], v[168:169], v[164:165], v[172:173] op_sel_hi:[1,0,1]
	v_cvt_pk_f32_fp8_sdwa v[172:173], v158 src0_sel:WORD_1
	v_pk_fma_f32 v[172:173], v[172:173], v[164:165], v[176:177] op_sel_hi:[1,0,1]
	v_cvt_pk_f32_fp8_e32 v[176:177], v159
	v_cvt_pk_f32_fp8_sdwa v[158:159], v159 src0_sel:WORD_1
	v_pk_fma_f32 v[176:177], v[176:177], v[164:165], v[192:193] op_sel_hi:[1,0,1]
	v_pk_fma_f32 v[158:159], v[158:159], v[164:165], v[166:167] op_sel_hi:[1,0,1]
	v_cvt_pk_f32_fp8_e32 v[166:167], v160
	v_pk_fma_f32 v[166:167], v[166:167], v[164:165], v[170:171] op_sel_hi:[1,0,1]
; __device__ __forceinline__ f32x2 fp8x2_lo(unsigned w) { return __builtin_amdgcn_cvt_pk_f32_fp8(w, false); }
; __device__ __forceinline__ f32x2 fp8x2_hi(unsigned w) { return __builtin_amdgcn_cvt_pk_f32_fp8(w, true); }
; #define PB_IDS(T) do { const unsigned* kp_ = KP + (size_t)(T) * 256; _Pragma("unroll") for (int qq = 0; qq < 4; ++qq) idv[qq] = *(const u32x4*)(kp_ + 4 * qq); } while (0)
; template <bool NT>
; __device__ __forceinline__ void peer_passB(const Args& a, const PeerWork w) {
;     ...
;     int t = peer_tok(w, q), t1 = peer_tok(w, min(q + qs, ql));
;     PB_IDS(t);
;     PB_GATHER(t, vr, cf, hv);
;     PB_IDS(t1);
; #pragma unroll 1
;     for (;; q += qs) {
;         u32x4 vrn[16]; f32x4 cfn[4]; f32x2 hn;
;         PB_GATHER(t1, vrn, cfn, hn);
;         const int t2 = peer_tok(w, min(q + 2 * qs, ql));
;         PB_IDS(t2);
;         f32x2 acc[8];
; #pragma unroll
;         for (int m = 0; m < 8; ++m) acc[m] = (f32x2){0.f, 0.f};
; #pragma unroll
;         for (int k = 0; k < 16; ++k) {
;             const unsigned ww[4] = {vr[k].x, vr[k].y, vr[k].z, vr[k].w};
;             const float c = cf[k >> 2][k & 3]; const f32x2 c2 = {c, c};
; #pragma unroll
;             for (int wd = 0; wd < 4; ++wd) { acc[2 * wd] = __builtin_elementwise_fma(fp8x2_lo(ww[wd]), c2, acc[2 * wd]); acc[2 * wd + 1] = __builtin_elementwise_fma(fp8x2_hi(ww[wd]), c2, acc[2 * wd + 1]); }
;         }
	v_cvt_pk_f32_fp8_sdwa v[170:171], v160 src0_sel:WORD_1
	v_pk_fma_f32 v[170:171], v[170:171], v[164:165], v[174:175] op_sel_hi:[1,0,1]
	v_cvt_pk_f32_fp8_e32 v[174:175], v161
	v_cvt_pk_f32_fp8_sdwa v[160:161], v161 src0_sel:WORD_1
	v_pk_fma_f32 v[174:175], v[174:175], v[164:165], v[194:195] op_sel_hi:[1,0,1]
	v_pk_fma_f32 v[160:161], v[160:161], v[164:165], v[162:163] op_sel_hi:[1,0,1]
	v_cvt_pk_f32_fp8_e32 v[162:163], v138
	v_cvt_pk_f32_fp8_sdwa v[164:165], v138 src0_sel:WORD_1
	v_pk_fma_f32 v[162:163], v[162:163], v[62:63], v[168:169] op_sel_hi:[1,0,1]
	v_cvt_pk_f32_fp8_e32 v[168:169], v139
	v_cvt_pk_f32_fp8_sdwa v[138:139], v139 src0_sel:WORD_1
	v_pk_fma_f32 v[164:165], v[164:165], v[62:63], v[172:173] op_sel_hi:[1,0,1]
	v_pk_fma_f32 v[168:169], v[168:169], v[62:63], v[176:177] op_sel_hi:[1,0,1]
	v_pk_fma_f32 v[138:139], v[138:139], v[62:63], v[158:159] op_sel_hi:[1,0,1]
	v_cvt_pk_f32_fp8_e32 v[158:159], v140
	v_pk_fma_f32 v[158:159], v[158:159], v[62:63], v[166:167] op_sel_hi:[1,0,1]
	v_cvt_pk_f32_fp8_sdwa v[166:167], v140 src0_sel:WORD_1
	v_pk_fma_f32 v[166:167], v[166:167], v[62:63], v[170:171] op_sel_hi:[1,0,1]
	v_cvt_pk_f32_fp8_e32 v[170:171], v141
	v_cvt_pk_f32_fp8_sdwa v[140:141], v141 src0_sel:WORD_1
	v_pk_fma_f32 v[170:171], v[170:171], v[62:63], v[174:175] op_sel_hi:[1,0,1]
	v_pk_fma_f32 v[140:141], v[140:141], v[62:63], v[160:161] op_sel_hi:[1,0,1]
	v_cvt_pk_f32_fp8_e32 v[160:161], v94
	v_pk_fma_f32 v[160:161], v[160:161], v[62:63], v[162:163] op_sel:[0,1,0]
	v_cvt_pk_f32_fp8_sdwa v[162:163], v94 src0_sel:WORD_1
	v_pk_fma_f32 v[162:163], v[162:163], v[62:63], v[164:165] op_sel:[0,1,0]
	v_cvt_pk_f32_fp8_e32 v[164:165], v95
	v_cvt_pk_f32_fp8_sdwa v[94:95], v95 src0_sel:WORD_1
	s_ashr_i32 s13, s12, 31
	v_pk_fma_f32 v[164:165], v[164:165], v[62:63], v[168:169] op_sel:[0,1,0]
	v_pk_fma_f32 v[94:95], v[94:95], v[62:63], v[138:139] op_sel:[0,1,0]
	v_cvt_pk_f32_fp8_e32 v[138:139], v96
	s_lshl_b64 s[12:13], s[12:13], 12
	s_add_i32 s18, s18, s22
	v_pk_fma_f32 v[138:139], v[138:139], v[62:63], v[158:159] op_sel:[0,1,0]
	v_cvt_pk_f32_fp8_sdwa v[158:159], v96 src0_sel:WORD_1
	s_cmpk_lt_i32 s18, 0x4000
	v_pk_fma_f32 v[158:159], v[158:159], v[62:63], v[166:167] op_sel:[0,1,0]
	v_cvt_pk_f32_fp8_e32 v[166:167], v97
	v_cvt_pk_f32_fp8_sdwa v[96:97], v97 src0_sel:WORD_1
	v_pk_fma_f32 v[166:167], v[166:167], v[62:63], v[170:171] op_sel:[0,1,0]
	v_pk_fma_f32 v[62:63], v[96:97], v[62:63], v[140:141] op_sel:[0,1,0]
	v_cvt_pk_f32_fp8_e32 v[96:97], v66
	v_cvt_pk_f32_fp8_sdwa v[140:141], v66 src0_sel:WORD_1
	v_pk_fma_f32 v[96:97], v[96:97], v[64:65], v[160:161] op_sel_hi:[1,0,1]
	v_cvt_pk_f32_fp8_e32 v[160:161], v67
	v_cvt_pk_f32_fp8_sdwa v[66:67], v67 src0_sel:WORD_1
	v_pk_fma_f32 v[140:141], v[140:141], v[64:65], v[162:163] op_sel_hi:[1,0,1]
	v_pk_fma_f32 v[160:161], v[160:161], v[64:65], v[164:165] op_sel_hi:[1,0,1]
	v_pk_fma_f32 v[66:67], v[66:67], v[64:65], v[94:95] op_sel_hi:[1,0,1]
	v_cvt_pk_f32_fp8_e32 v[94:95], v68
	v_pk_fma_f32 v[94:95], v[94:95], v[64:65], v[138:139] op_sel_hi:[1,0,1]
	v_cvt_pk_f32_fp8_sdwa v[138:139], v68 src0_sel:WORD_1
	v_pk_fma_f32 v[138:139], v[138:139], v[64:65], v[158:159] op_sel_hi:[1,0,1]
	v_cvt_pk_f32_fp8_e32 v[158:159], v69
	v_cvt_pk_f32_fp8_sdwa v[68:69], v69 src0_sel:WORD_1
	v_pk_fma_f32 v[158:159], v[158:159], v[64:65], v[166:167] op_sel_hi:[1,0,1]
	v_pk_fma_f32 v[62:63], v[68:69], v[64:65], v[62:63] op_sel_hi:[1,0,1]
	v_cvt_pk_f32_fp8_e32 v[68:69], v58
	v_mov_b32_e32 v64, v65
	v_pk_fma_f32 v[68:69], v[68:69], v[64:65], v[96:97] op_sel_hi:[1,0,1]
	v_cvt_pk_f32_fp8_sdwa v[96:97], v58 src0_sel:WORD_1
	v_pk_fma_f32 v[96:97], v[96:97], v[64:65], v[140:141] op_sel_hi:[1,0,1]
	v_cvt_pk_f32_fp8_e32 v[140:141], v59
	v_cvt_pk_f32_fp8_sdwa v[58:59], v59 src0_sel:WORD_1
	v_pk_fma_f32 v[140:141], v[140:141], v[64:65], v[160:161] op_sel_hi:[1,0,1]
	v_pk_fma_f32 v[58:59], v[58:59], v[64:65], v[66:67] op_sel_hi:[1,0,1]
	v_cvt_pk_f32_fp8_e32 v[66:67], v60
	v_pk_fma_f32 v[66:67], v[66:67], v[64:65], v[94:95] op_sel_hi:[1,0,1]
	v_cvt_pk_f32_fp8_sdwa v[94:95], v60 src0_sel:WORD_1
	v_pk_fma_f32 v[94:95], v[94:95], v[64:65], v[138:139] op_sel_hi:[1,0,1]
	v_cvt_pk_f32_fp8_e32 v[138:139], v61
	v_cvt_pk_f32_fp8_sdwa v[60:61], v61 src0_sel:WORD_1
	v_pk_fma_f32 v[138:139], v[138:139], v[64:65], v[158:159] op_sel_hi:[1,0,1]
	v_pk_fma_f32 v[60:61], v[60:61], v[64:65], v[62:63] op_sel_hi:[1,0,1]
	v_cvt_pk_f32_fp8_e32 v[62:63], v54
	v_cvt_pk_f32_fp8_sdwa v[64:65], v54 src0_sel:WORD_1
	v_pk_fma_f32 v[62:63], v[62:63], v[38:39], v[68:69] op_sel_hi:[1,0,1]
	v_cvt_pk_f32_fp8_e32 v[68:69], v55
	v_cvt_pk_f32_fp8_sdwa v[54:55], v55 src0_sel:WORD_1
	v_pk_fma_f32 v[64:65], v[64:65], v[38:39], v[96:97] op_sel_hi:[1,0,1]
	v_pk_fma_f32 v[68:69], v[68:69], v[38:39], v[140:141] op_sel_hi:[1,0,1]
	v_pk_fma_f32 v[54:55], v[54:55], v[38:39], v[58:59] op_sel_hi:[1,0,1]
	v_cvt_pk_f32_fp8_e32 v[58:59], v56
	v_pk_fma_f32 v[58:59], v[58:59], v[38:39], v[66:67] op_sel_hi:[1,0,1]
	v_cvt_pk_f32_fp8_sdwa v[66:67], v56 src0_sel:WORD_1
	v_pk_fma_f32 v[66:67], v[66:67], v[38:39], v[94:95] op_sel_hi:[1,0,1]
	v_cvt_pk_f32_fp8_e32 v[94:95], v57
	v_cvt_pk_f32_fp8_sdwa v[56:57], v57 src0_sel:WORD_1
	v_pk_fma_f32 v[94:95], v[94:95], v[38:39], v[138:139] op_sel_hi:[1,0,1]
	v_pk_fma_f32 v[56:57], v[56:57], v[38:39], v[60:61] op_sel_hi:[1,0,1]
	v_cvt_pk_f32_fp8_e32 v[60:61], v50
	v_pk_fma_f32 v[60:61], v[60:61], v[38:39], v[62:63] op_sel:[0,1,0]
	v_cvt_pk_f32_fp8_sdwa v[62:63], v50 src0_sel:WORD_1
	v_pk_fma_f32 v[62:63], v[62:63], v[38:39], v[64:65] op_sel:[0,1,0]
	v_cvt_pk_f32_fp8_e32 v[64:65], v51
	v_cvt_pk_f32_fp8_sdwa v[50:51], v51 src0_sel:WORD_1
; __device__ __forceinline__ f32x2 fp8x2_lo(unsigned w) { return __builtin_amdgcn_cvt_pk_f32_fp8(w, false); }
; __device__ __forceinline__ f32x2 fp8x2_hi(unsigned w) { return __builtin_amdgcn_cvt_pk_f32_fp8(w, true); }
; template <bool NT>
; __device__ __forceinline__ void peer_passB(const Args& a, const PeerWork w) {
;     ...
;         for (int k = 0; k < 16; ++k) {
;             const unsigned ww[4] = {vr[k].x, vr[k].y, vr[k].z, vr[k].w};
;             const float c = cf[k >> 2][k & 3]; const f32x2 c2 = {c, c};
; #pragma unroll
;             for (int wd = 0; wd < 4; ++wd) { acc[2 * wd] = __builtin_elementwise_fma(fp8x2_lo(ww[wd]), c2, acc[2 * wd]); acc[2 * wd + 1] = __builtin_elementwise_fma(fp8x2_hi(ww[wd]), c2, acc[2 * wd + 1]); }
;         }
	v_pk_fma_f32 v[64:65], v[64:65], v[38:39], v[68:69] op_sel:[0,1,0]
	v_pk_fma_f32 v[50:51], v[50:51], v[38:39], v[54:55] op_sel:[0,1,0]
	v_cvt_pk_f32_fp8_e32 v[54:55], v52
	v_pk_fma_f32 v[54:55], v[54:55], v[38:39], v[58:59] op_sel:[0,1,0]
	v_cvt_pk_f32_fp8_sdwa v[58:59], v52 src0_sel:WORD_1
	v_pk_fma_f32 v[58:59], v[58:59], v[38:39], v[66:67] op_sel:[0,1,0]
	v_cvt_pk_f32_fp8_e32 v[66:67], v53
	v_cvt_pk_f32_fp8_sdwa v[52:53], v53 src0_sel:WORD_1
	v_pk_fma_f32 v[66:67], v[66:67], v[38:39], v[94:95] op_sel:[0,1,0]
	v_pk_fma_f32 v[38:39], v[52:53], v[38:39], v[56:57] op_sel:[0,1,0]
	v_cvt_pk_f32_fp8_e32 v[52:53], v46
	v_cvt_pk_f32_fp8_sdwa v[56:57], v46 src0_sel:WORD_1
	v_pk_fma_f32 v[52:53], v[52:53], v[40:41], v[60:61] op_sel_hi:[1,0,1]
	v_cvt_pk_f32_fp8_e32 v[60:61], v47
	v_cvt_pk_f32_fp8_sdwa v[46:47], v47 src0_sel:WORD_1
	v_pk_fma_f32 v[56:57], v[56:57], v[40:41], v[62:63] op_sel_hi:[1,0,1]
	v_pk_fma_f32 v[60:61], v[60:61], v[40:41], v[64:65] op_sel_hi:[1,0,1]
	v_pk_fma_f32 v[46:47], v[46:47], v[40:41], v[50:51] op_sel_hi:[1,0,1]
	v_cvt_pk_f32_fp8_e32 v[50:51], v48
	v_pk_fma_f32 v[50:51], v[50:51], v[40:41], v[54:55] op_sel_hi:[1,0,1]
	v_cvt_pk_f32_fp8_sdwa v[54:55], v48 src0_sel:WORD_1
	v_pk_fma_f32 v[54:55], v[54:55], v[40:41], v[58:59] op_sel_hi:[1,0,1]
	v_cvt_pk_f32_fp8_e32 v[58:59], v49
	v_cvt_pk_f32_fp8_sdwa v[48:49], v49 src0_sel:WORD_1
	v_pk_fma_f32 v[58:59], v[58:59], v[40:41], v[66:67] op_sel_hi:[1,0,1]
	v_pk_fma_f32 v[38:39], v[48:49], v[40:41], v[38:39] op_sel_hi:[1,0,1]
	v_cvt_pk_f32_fp8_e32 v[48:49], v42
	v_mov_b32_e32 v40, v41
	v_pk_fma_f32 v[48:49], v[48:49], v[40:41], v[52:53] op_sel_hi:[1,0,1]
	v_cvt_pk_f32_fp8_sdwa v[52:53], v42 src0_sel:WORD_1
	v_pk_fma_f32 v[52:53], v[52:53], v[40:41], v[56:57] op_sel_hi:[1,0,1]
	v_cvt_pk_f32_fp8_e32 v[56:57], v43
	v_cvt_pk_f32_fp8_sdwa v[42:43], v43 src0_sel:WORD_1
	v_pk_fma_f32 v[56:57], v[56:57], v[40:41], v[60:61] op_sel_hi:[1,0,1]
	v_pk_fma_f32 v[42:43], v[42:43], v[40:41], v[46:47] op_sel_hi:[1,0,1]
	v_cvt_pk_f32_fp8_e32 v[46:47], v44
	v_pk_fma_f32 v[46:47], v[46:47], v[40:41], v[50:51] op_sel_hi:[1,0,1]
	v_cvt_pk_f32_fp8_sdwa v[50:51], v44 src0_sel:WORD_1
	v_pk_fma_f32 v[50:51], v[50:51], v[40:41], v[54:55] op_sel_hi:[1,0,1]
	v_cvt_pk_f32_fp8_e32 v[54:55], v45
	v_cvt_pk_f32_fp8_sdwa v[44:45], v45 src0_sel:WORD_1
	v_pk_fma_f32 v[54:55], v[54:55], v[40:41], v[58:59] op_sel_hi:[1,0,1]
	v_pk_fma_f32 v[38:39], v[44:45], v[40:41], v[38:39] op_sel_hi:[1,0,1]
	v_cvt_pk_f32_fp8_e32 v[40:41], v34
	v_cvt_pk_f32_fp8_sdwa v[44:45], v34 src0_sel:WORD_1
	v_pk_fma_f32 v[40:41], v[40:41], v[22:23], v[48:49] op_sel_hi:[1,0,1]
	v_cvt_pk_f32_fp8_e32 v[48:49], v35
	v_cvt_pk_f32_fp8_sdwa v[34:35], v35 src0_sel:WORD_1
	v_pk_fma_f32 v[44:45], v[44:45], v[22:23], v[52:53] op_sel_hi:[1,0,1]
	v_pk_fma_f32 v[48:49], v[48:49], v[22:23], v[56:57] op_sel_hi:[1,0,1]
	v_pk_fma_f32 v[34:35], v[34:35], v[22:23], v[42:43] op_sel_hi:[1,0,1]
	v_cvt_pk_f32_fp8_e32 v[42:43], v36
	v_pk_fma_f32 v[42:43], v[42:43], v[22:23], v[46:47] op_sel_hi:[1,0,1]
	v_cvt_pk_f32_fp8_sdwa v[46:47], v36 src0_sel:WORD_1
	v_pk_fma_f32 v[46:47], v[46:47], v[22:23], v[50:51] op_sel_hi:[1,0,1]
	v_cvt_pk_f32_fp8_e32 v[50:51], v37
	v_cvt_pk_f32_fp8_sdwa v[36:37], v37 src0_sel:WORD_1
	v_pk_fma_f32 v[50:51], v[50:51], v[22:23], v[54:55] op_sel_hi:[1,0,1]
	v_pk_fma_f32 v[36:37], v[36:37], v[22:23], v[38:39] op_sel_hi:[1,0,1]
	v_cvt_pk_f32_fp8_e32 v[38:39], v30
	v_pk_fma_f32 v[38:39], v[38:39], v[22:23], v[40:41] op_sel:[0,1,0]
	v_cvt_pk_f32_fp8_sdwa v[40:41], v30 src0_sel:WORD_1
	v_pk_fma_f32 v[40:41], v[40:41], v[22:23], v[44:45] op_sel:[0,1,0]
	v_cvt_pk_f32_fp8_e32 v[44:45], v31
	v_cvt_pk_f32_fp8_sdwa v[30:31], v31 src0_sel:WORD_1
	v_pk_fma_f32 v[44:45], v[44:45], v[22:23], v[48:49] op_sel:[0,1,0]
	v_pk_fma_f32 v[30:31], v[30:31], v[22:23], v[34:35] op_sel:[0,1,0]
	v_cvt_pk_f32_fp8_e32 v[34:35], v32
	v_pk_fma_f32 v[34:35], v[34:35], v[22:23], v[42:43] op_sel:[0,1,0]
	v_cvt_pk_f32_fp8_sdwa v[42:43], v32 src0_sel:WORD_1
	v_pk_fma_f32 v[42:43], v[42:43], v[22:23], v[46:47] op_sel:[0,1,0]
	v_cvt_pk_f32_fp8_e32 v[46:47], v33
	v_cvt_pk_f32_fp8_sdwa v[32:33], v33 src0_sel:WORD_1
	v_pk_fma_f32 v[46:47], v[46:47], v[22:23], v[50:51] op_sel:[0,1,0]
	v_pk_fma_f32 v[22:23], v[32:33], v[22:23], v[36:37] op_sel:[0,1,0]
	v_cvt_pk_f32_fp8_e32 v[32:33], v26
	v_cvt_pk_f32_fp8_sdwa v[36:37], v26 src0_sel:WORD_1
	v_pk_fma_f32 v[32:33], v[32:33], v[24:25], v[38:39] op_sel_hi:[1,0,1]
	v_cvt_pk_f32_fp8_e32 v[38:39], v27
	v_cvt_pk_f32_fp8_sdwa v[26:27], v27 src0_sel:WORD_1
	v_pk_fma_f32 v[36:37], v[36:37], v[24:25], v[40:41] op_sel_hi:[1,0,1]
	v_cvt_pk_f32_fp8_e32 v[40:41], v29
	v_pk_fma_f32 v[38:39], v[38:39], v[24:25], v[44:45] op_sel_hi:[1,0,1]
	v_pk_fma_f32 v[26:27], v[26:27], v[24:25], v[30:31] op_sel_hi:[1,0,1]
	v_cvt_pk_f32_fp8_e32 v[30:31], v28
	v_pk_fma_f32 v[40:41], v[40:41], v[24:25], v[46:47] op_sel_hi:[1,0,1]
	v_pk_fma_f32 v[30:31], v[30:31], v[24:25], v[34:35] op_sel_hi:[1,0,1]
	v_cvt_pk_f32_fp8_sdwa v[34:35], v28 src0_sel:WORD_1
	v_cvt_pk_f32_fp8_sdwa v[28:29], v29 src0_sel:WORD_1
	v_pk_fma_f32 v[34:35], v[34:35], v[24:25], v[42:43] op_sel_hi:[1,0,1]
	v_pk_fma_f32 v[22:23], v[28:29], v[24:25], v[22:23] op_sel_hi:[1,0,1]
	v_cvt_pk_f32_fp8_e32 v[28:29], v18
	v_mov_b32_e32 v24, v25
	v_pk_fma_f32 v[28:29], v[28:29], v[24:25], v[32:33] op_sel_hi:[1,0,1]
	v_cvt_pk_f32_fp8_sdwa v[32:33], v18 src0_sel:WORD_1
	v_pk_fma_f32 v[32:33], v[32:33], v[24:25], v[36:37] op_sel_hi:[1,0,1]
	v_cvt_pk_f32_fp8_e32 v[36:37], v19
	v_cvt_pk_f32_fp8_sdwa v[18:19], v19 src0_sel:WORD_1
	v_pk_fma_f32 v[36:37], v[36:37], v[24:25], v[38:39] op_sel_hi:[1,0,1]
; template <int CTRL> __device__ __forceinline__ float dpp_f(float x) { return __uint_as_float((unsigned)__builtin_amdgcn_update_dpp(0, (int)__float_as_uint(x), CTRL, 0xf, 0xf, false)); }
; __device__ __forceinline__ f32x2 fp8x2_lo(unsigned w) { return __builtin_amdgcn_cvt_pk_f32_fp8(w, false); }
; __device__ __forceinline__ f32x2 fp8x2_hi(unsigned w) { return __builtin_amdgcn_cvt_pk_f32_fp8(w, true); }
; template <bool NT>
; __device__ __forceinline__ void peer_passB(const Args& a, const PeerWork w) {
;     ...
;     int t = peer_tok(w, q), t1 = peer_tok(w, min(q + qs, ql));
;     PB_IDS(t);
;     PB_GATHER(t, vr, cf, hv);
;     PB_IDS(t1);
; #pragma unroll 1
;     for (;; q += qs) {
;         u32x4 vrn[16]; f32x4 cfn[4]; f32x2 hn;
;         PB_GATHER(t1, vrn, cfn, hn);
;         const int t2 = peer_tok(w, min(q + 2 * qs, ql));
;         PB_IDS(t2);
;         f32x2 acc[8];
; #pragma unroll
;         for (int m = 0; m < 8; ++m) acc[m] = (f32x2){0.f, 0.f};
; #pragma unroll
;         for (int k = 0; k < 16; ++k) {
;             const unsigned ww[4] = {vr[k].x, vr[k].y, vr[k].z, vr[k].w};
;             const float c = cf[k >> 2][k & 3]; const f32x2 c2 = {c, c};
; #pragma unroll
;             for (int wd = 0; wd < 4; ++wd) { acc[2 * wd] = __builtin_elementwise_fma(fp8x2_lo(ww[wd]), c2, acc[2 * wd]); acc[2 * wd + 1] = __builtin_elementwise_fma(fp8x2_hi(ww[wd]), c2, acc[2 * wd + 1]); }
;     ...
;         float w8[8], w4[4], w2[2];
; #pragma unroll
;         for (int m = 0; m < 8; ++m) { const auto sw = __builtin_amdgcn_permlane32_swap(__float_as_uint(acc[m >> 1][m & 1]), __float_as_uint(acc[(m + 8) >> 1][m & 1]), false, false); w8[m] = __uint_as_float(sw[0]) + __uint_as_float(sw[1]); }
; #pragma unroll
;         for (int m = 0; m < 4; ++m) { const auto sw = __builtin_amdgcn_permlane16_swap(__float_as_uint(w8[m]), __float_as_uint(w8[m + 4]), false, false); w4[m] = __uint_as_float(sw[0]) + __uint_as_float(sw[1]); }
;         { const bool up = (lane & 8) != 0;
; #pragma unroll
;           for (int m = 0; m < 2; ++m) { const float keep = up ? w4[m + 2] : w4[m], send = up ? w4[m] : w4[m + 2]; w2[m] = keep + dpp_f<0x128>(send); } }
;         *(f32x2*)(Y + (size_t)t * DM) = (f32x2){hv[0] + w2[0], hv[1] + w2[1]};
;         if (q + qs > ql) break;
	v_pk_fma_f32 v[18:19], v[18:19], v[24:25], v[26:27] op_sel_hi:[1,0,1]
	v_cvt_pk_f32_fp8_e32 v[26:27], v20
	v_pk_fma_f32 v[26:27], v[26:27], v[24:25], v[30:31] op_sel_hi:[1,0,1]
	v_cvt_pk_f32_fp8_sdwa v[30:31], v20 src0_sel:WORD_1
	s_nop 0
	v_permlane32_swap_b32_e32 v28, v26
	v_permlane32_swap_b32_e32 v29, v27
	v_pk_fma_f32 v[30:31], v[30:31], v[24:25], v[34:35] op_sel_hi:[1,0,1]
	v_cvt_pk_f32_fp8_e32 v[34:35], v21
	v_cvt_pk_f32_fp8_sdwa v[20:21], v21 src0_sel:WORD_1
	v_permlane32_swap_b32_e32 v32, v30
	v_pk_fma_f32 v[34:35], v[34:35], v[24:25], v[40:41] op_sel_hi:[1,0,1]
	v_pk_fma_f32 v[20:21], v[20:21], v[24:25], v[22:23] op_sel_hi:[1,0,1]
	v_permlane32_swap_b32_e32 v33, v31
	v_permlane32_swap_b32_e32 v36, v34
	v_permlane32_swap_b32_e32 v37, v35
	v_permlane32_swap_b32_e32 v18, v20
	v_permlane32_swap_b32_e32 v19, v21
	v_add_f32_e32 v22, v28, v26
	v_add_f32_e32 v23, v29, v27
	v_add_f32_e32 v24, v32, v30
	v_add_f32_e32 v25, v33, v31
	v_add_f32_e32 v26, v36, v34
	v_add_f32_e32 v27, v37, v35
	v_add_f32_e32 v18, v18, v20
	v_add_f32_e32 v19, v19, v21
	v_permlane16_swap_b32_e32 v22, v26
	v_permlane16_swap_b32_e32 v23, v27
	v_permlane16_swap_b32_e32 v24, v18
	v_permlane16_swap_b32_e32 v25, v19
	v_pk_add_f32 v[20:21], v[22:23], v[26:27]
	v_pk_add_f32 v[18:19], v[24:25], v[18:19]
	v_mov_b32_e32 v22, 0
	v_cndmask_b32_e32 v23, v20, v18, vcc
	v_cndmask_b32_e32 v24, v18, v20, vcc
	v_cndmask_b32_e32 v18, v21, v19, vcc
	v_mov_b32_dpp v22, v23 row_ror:8 row_mask:0xf bank_mask:0xf
	v_mov_b32_e32 v23, 0
	v_cndmask_b32_e32 v25, v19, v21, vcc
	v_lshl_add_u64 v[20:21], v[186:187], 0, s[12:13]
	v_mov_b32_dpp v23, v18 row_ror:8 row_mask:0xf bank_mask:0xf
	v_pk_add_f32 v[18:19], v[24:25], v[22:23]
	v_pk_add_f32 v[18:19], v[190:191], v[18:19]
	global_store_dwordx2 v[20:21], v[18:19], off
	s_mov_b32 s12, s14
	s_cbranch_scc0 .LBB0_1588
	s_waitcnt vmcnt(3)
	v_lshl_or_b32 v6, v6, 7, v1
	v_lshl_or_b32 v2, v2, 7, v1
	s_waitcnt vmcnt(1)
	v_lshl_or_b32 v14, v14, 7, v1
	v_lshl_or_b32 v10, v10, 7, v1
	global_load_dwordx4 v[54:57], v6, s[4:5]
	global_load_dwordx4 v[34:37], v2, s[4:5]
	v_lshl_or_b32 v6, v7, 7, v1
	v_lshl_or_b32 v2, v3, 7, v1
	s_mov_b32 s14, s6
	global_load_dwordx4 v[174:177], v14, s[4:5]
	global_load_dwordx4 v[138:141], v10, s[4:5]
	v_lshl_or_b32 v14, v15, 7, v1
	v_lshl_or_b32 v10, v11, 7, v1
	global_load_dwordx4 v[50:53], v6, s[4:5]
	global_load_dwordx4 v[30:33], v2, s[4:5]
	v_lshl_or_b32 v6, v8, 7, v1
	v_lshl_or_b32 v2, v4, 7, v1
	s_ashr_i32 s15, s6, 31
	global_load_dwordx4 v[170:173], v14, s[4:5]
	global_load_dwordx4 v[94:97], v10, s[4:5]
	v_lshl_or_b32 v14, v16, 7, v1
	v_lshl_or_b32 v10, v12, 7, v1
	global_load_dwordx4 v[46:49], v6, s[4:5]
	global_load_dwordx4 v[26:29], v2, s[4:5]
	v_lshl_or_b32 v6, v9, 7, v1
	v_lshl_or_b32 v2, v5, 7, v1
	s_lshl_b64 s[6:7], s[14:15], 9
	global_load_dwordx4 v[166:169], v14, s[4:5]
	global_load_dwordx4 v[66:69], v10, s[4:5]
	v_lshl_or_b32 v14, v17, 7, v1
	v_lshl_or_b32 v10, v13, 7, v1
	global_load_dwordx4 v[42:45], v6, s[4:5]
	global_load_dwordx4 v[18:21], v2, s[4:5]
	v_lshl_add_u64 v[2:3], v[184:185], 0, s[6:7]
	s_lshl_b64 s[6:7], s[14:15], 12
	global_load_dwordx4 v[158:161], v14, s[4:5]
	global_load_dwordx4 v[58:61], v10, s[4:5]
	global_load_dwordx4 v[22:25], v[2:3], off offset:48
	global_load_dwordx4 v[38:41], v[2:3], off offset:32
	global_load_dwordx4 v[62:65], v[2:3], off offset:16
	global_load_dwordx4 v[162:165], v[2:3], off
	v_lshl_add_u64 v[2:3], v[182:183], 0, s[6:7]
	s_add_i32 s6, s11, s18
	s_min_i32 s6, s6, 0x3fff
	s_ashr_i32 s7, s6, 31
	s_lshl_b64 s[28:29], s[6:7], 10
	v_lshl_add_u64 v[14:15], v[180:181], 0, s[28:29]
	global_load_dwordx2 v[190:191], v[2:3], off
	global_load_dwordx4 v[2:5], v[14:15], off offset:48
	global_load_dwordx4 v[6:9], v[14:15], off offset:32
	global_load_dwordx4 v[10:13], v[14:15], off offset:16
	global_load_dwordx4 v[14:17], v[14:15], off
	v_cvt_pk_f32_fp8_e32 v[192:193], v70
	v_cvt_pk_f32_fp8_e32 v[204:205], v74
	v_cvt_pk_f32_fp8_sdwa v[194:195], v70 src0_sel:WORD_1
	v_cvt_pk_f32_fp8_e32 v[196:197], v71
	v_pk_fma_f32 v[192:193], v[192:193], v[154:155], 0 op_sel_hi:[1,0,0]
	v_cvt_pk_f32_fp8_sdwa v[70:71], v71 src0_sel:WORD_1
	v_pk_fma_f32 v[192:193], v[204:205], v[154:155], v[192:193] op_sel:[0,1,0]
	v_cvt_pk_f32_fp8_sdwa v[204:205], v74 src0_sel:WORD_1
	v_pk_fma_f32 v[194:195], v[194:195], v[154:155], 0 op_sel_hi:[1,0,0]
	v_pk_fma_f32 v[70:71], v[70:71], v[154:155], 0 op_sel_hi:[1,0,0]
	v_cvt_pk_f32_fp8_e32 v[198:199], v72
	v_pk_fma_f32 v[194:195], v[204:205], v[154:155], v[194:195] op_sel:[0,1,0]
	v_cvt_pk_f32_fp8_e32 v[204:205], v75
	v_cvt_pk_f32_fp8_sdwa v[74:75], v75 src0_sel:WORD_1
	v_pk_fma_f32 v[198:199], v[198:199], v[154:155], 0 op_sel_hi:[1,0,0]
	v_cvt_pk_f32_fp8_sdwa v[200:201], v72 src0_sel:WORD_1
	v_cvt_pk_f32_fp8_e32 v[202:203], v73
	v_pk_fma_f32 v[74:75], v[74:75], v[154:155], v[70:71] op_sel:[0,1,0]
	v_cvt_pk_f32_fp8_e32 v[70:71], v76
	v_pk_fma_f32 v[200:201], v[200:201], v[154:155], 0 op_sel_hi:[1,0,0]
	v_cvt_pk_f32_fp8_sdwa v[72:73], v73 src0_sel:WORD_1
	v_pk_fma_f32 v[196:197], v[196:197], v[154:155], 0 op_sel_hi:[1,0,0]
	v_pk_fma_f32 v[70:71], v[70:71], v[154:155], v[198:199] op_sel:[0,1,0]
	v_cvt_pk_f32_fp8_sdwa v[198:199], v76 src0_sel:WORD_1
	v_pk_fma_f32 v[202:203], v[202:203], v[154:155], 0 op_sel_hi:[1,0,0]
	v_pk_fma_f32 v[72:73], v[72:73], v[154:155], 0 op_sel_hi:[1,0,0]
	v_pk_fma_f32 v[196:197], v[204:205], v[154:155], v[196:197] op_sel:[0,1,0]
	v_pk_fma_f32 v[198:199], v[198:199], v[154:155], v[200:201] op_sel:[0,1,0]
	v_cvt_pk_f32_fp8_e32 v[200:201], v77
	v_cvt_pk_f32_fp8_sdwa v[76:77], v77 src0_sel:WORD_1
	v_pk_fma_f32 v[200:201], v[200:201], v[154:155], v[202:203] op_sel:[0,1,0]
; __device__ __forceinline__ f32x2 fp8x2_lo(unsigned w) { return __builtin_amdgcn_cvt_pk_f32_fp8(w, false); }
; __device__ __forceinline__ f32x2 fp8x2_hi(unsigned w) { return __builtin_amdgcn_cvt_pk_f32_fp8(w, true); }
; #define PB_IDS(T) do { const unsigned* kp_ = KP + (size_t)(T) * 256; _Pragma("unroll") for (int qq = 0; qq < 4; ++qq) idv[qq] = *(const u32x4*)(kp_ + 4 * qq); } while (0)
; template <bool NT>
; __device__ __forceinline__ void peer_passB(const Args& a, const PeerWork w) {
;     ...
;     int t = peer_tok(w, q), t1 = peer_tok(w, min(q + qs, ql));
;     PB_IDS(t);
;     PB_GATHER(t, vr, cf, hv);
;     PB_IDS(t1);
; #pragma unroll 1
;     for (;; q += qs) {
;         u32x4 vrn[16]; f32x4 cfn[4]; f32x2 hn;
;         PB_GATHER(t1, vrn, cfn, hn);
;         const int t2 = peer_tok(w, min(q + 2 * qs, ql));
;         PB_IDS(t2);
;         f32x2 acc[8];
; #pragma unroll
;         for (int m = 0; m < 8; ++m) acc[m] = (f32x2){0.f, 0.f};
; #pragma unroll
;         for (int k = 0; k < 16; ++k) {
;             const unsigned ww[4] = {vr[k].x, vr[k].y, vr[k].z, vr[k].w};
;             const float c = cf[k >> 2][k & 3]; const f32x2 c2 = {c, c};
; #pragma unroll
;             for (int wd = 0; wd < 4; ++wd) { acc[2 * wd] = __builtin_elementwise_fma(fp8x2_lo(ww[wd]), c2, acc[2 * wd]); acc[2 * wd + 1] = __builtin_elementwise_fma(fp8x2_hi(ww[wd]), c2, acc[2 * wd + 1]); }
;         }
	v_pk_fma_f32 v[154:155], v[76:77], v[154:155], v[72:73] op_sel:[0,1,0]
	v_cvt_pk_f32_fp8_e32 v[76:77], v78
	v_cvt_pk_f32_fp8_sdwa v[72:73], v78 src0_sel:WORD_1
	v_pk_fma_f32 v[76:77], v[76:77], v[156:157], v[192:193] op_sel_hi:[1,0,1]
	v_cvt_pk_f32_fp8_e32 v[192:193], v79
	v_cvt_pk_f32_fp8_sdwa v[78:79], v79 src0_sel:WORD_1
	v_pk_fma_f32 v[72:73], v[72:73], v[156:157], v[194:195] op_sel_hi:[1,0,1]
	v_cvt_pk_f32_fp8_e32 v[194:195], v81
	v_pk_fma_f32 v[192:193], v[192:193], v[156:157], v[196:197] op_sel_hi:[1,0,1]
	v_pk_fma_f32 v[78:79], v[78:79], v[156:157], v[74:75] op_sel_hi:[1,0,1]
	v_cvt_pk_f32_fp8_e32 v[74:75], v80
	v_pk_fma_f32 v[194:195], v[194:195], v[156:157], v[200:201] op_sel_hi:[1,0,1]
	v_pk_fma_f32 v[74:75], v[74:75], v[156:157], v[70:71] op_sel_hi:[1,0,1]
	v_cvt_pk_f32_fp8_sdwa v[70:71], v80 src0_sel:WORD_1
	v_cvt_pk_f32_fp8_sdwa v[80:81], v81 src0_sel:WORD_1
	v_pk_fma_f32 v[70:71], v[70:71], v[156:157], v[198:199] op_sel_hi:[1,0,1]
	v_pk_fma_f32 v[154:155], v[80:81], v[156:157], v[154:155] op_sel_hi:[1,0,1]
	v_cvt_pk_f32_fp8_e32 v[80:81], v82
	v_mov_b32_e32 v156, v157
	v_pk_fma_f32 v[80:81], v[80:81], v[156:157], v[76:77] op_sel_hi:[1,0,1]
	v_cvt_pk_f32_fp8_sdwa v[76:77], v82 src0_sel:WORD_1
	v_pk_fma_f32 v[76:77], v[76:77], v[156:157], v[72:73] op_sel_hi:[1,0,1]
	v_cvt_pk_f32_fp8_e32 v[72:73], v83
	v_cvt_pk_f32_fp8_sdwa v[82:83], v83 src0_sel:WORD_1
	v_pk_fma_f32 v[72:73], v[72:73], v[156:157], v[192:193] op_sel_hi:[1,0,1]
	v_pk_fma_f32 v[82:83], v[82:83], v[156:157], v[78:79] op_sel_hi:[1,0,1]
	v_cvt_pk_f32_fp8_e32 v[78:79], v84
	v_pk_fma_f32 v[78:79], v[78:79], v[156:157], v[74:75] op_sel_hi:[1,0,1]
	v_cvt_pk_f32_fp8_sdwa v[74:75], v84 src0_sel:WORD_1
	v_pk_fma_f32 v[74:75], v[74:75], v[156:157], v[70:71] op_sel_hi:[1,0,1]
	v_cvt_pk_f32_fp8_e32 v[70:71], v85
	v_cvt_pk_f32_fp8_sdwa v[84:85], v85 src0_sel:WORD_1
	v_pk_fma_f32 v[70:71], v[70:71], v[156:157], v[194:195] op_sel_hi:[1,0,1]
	v_pk_fma_f32 v[84:85], v[84:85], v[156:157], v[154:155] op_sel_hi:[1,0,1]
	v_cvt_pk_f32_fp8_e32 v[154:155], v86
	v_cvt_pk_f32_fp8_sdwa v[156:157], v86 src0_sel:WORD_1
	v_pk_fma_f32 v[154:155], v[154:155], v[150:151], v[80:81] op_sel_hi:[1,0,1]
	v_cvt_pk_f32_fp8_e32 v[80:81], v87
	v_cvt_pk_f32_fp8_sdwa v[86:87], v87 src0_sel:WORD_1
	v_pk_fma_f32 v[156:157], v[156:157], v[150:151], v[76:77] op_sel_hi:[1,0,1]
	v_pk_fma_f32 v[80:81], v[80:81], v[150:151], v[72:73] op_sel_hi:[1,0,1]
	v_pk_fma_f32 v[86:87], v[86:87], v[150:151], v[82:83] op_sel_hi:[1,0,1]
	v_cvt_pk_f32_fp8_e32 v[82:83], v88
	v_pk_fma_f32 v[82:83], v[82:83], v[150:151], v[78:79] op_sel_hi:[1,0,1]
	v_cvt_pk_f32_fp8_sdwa v[78:79], v88 src0_sel:WORD_1
	v_pk_fma_f32 v[78:79], v[78:79], v[150:151], v[74:75] op_sel_hi:[1,0,1]
	v_cvt_pk_f32_fp8_e32 v[74:75], v89
	v_cvt_pk_f32_fp8_sdwa v[88:89], v89 src0_sel:WORD_1
	v_pk_fma_f32 v[74:75], v[74:75], v[150:151], v[70:71] op_sel_hi:[1,0,1]
	v_pk_fma_f32 v[88:89], v[88:89], v[150:151], v[84:85] op_sel_hi:[1,0,1]
	v_cvt_pk_f32_fp8_e32 v[84:85], v90
	v_pk_fma_f32 v[84:85], v[84:85], v[150:151], v[154:155] op_sel:[0,1,0]
	v_cvt_pk_f32_fp8_sdwa v[154:155], v90 src0_sel:WORD_1
	v_pk_fma_f32 v[154:155], v[154:155], v[150:151], v[156:157] op_sel:[0,1,0]
	v_cvt_pk_f32_fp8_e32 v[156:157], v91
	v_cvt_pk_f32_fp8_sdwa v[90:91], v91 src0_sel:WORD_1
	s_ashr_i32 s13, s12, 31
	v_pk_fma_f32 v[156:157], v[156:157], v[150:151], v[80:81] op_sel:[0,1,0]
	v_pk_fma_f32 v[90:91], v[90:91], v[150:151], v[86:87] op_sel:[0,1,0]
	v_cvt_pk_f32_fp8_e32 v[86:87], v92
	s_lshl_b64 s[12:13], s[12:13], 12
	s_add_i32 s18, s18, s22
	v_pk_fma_f32 v[86:87], v[86:87], v[150:151], v[82:83] op_sel:[0,1,0]
	v_cvt_pk_f32_fp8_sdwa v[82:83], v92 src0_sel:WORD_1
	s_cmpk_lt_i32 s18, 0x4000
	v_pk_fma_f32 v[82:83], v[82:83], v[150:151], v[78:79] op_sel:[0,1,0]
	v_cvt_pk_f32_fp8_e32 v[78:79], v93
	v_cvt_pk_f32_fp8_sdwa v[92:93], v93 src0_sel:WORD_1
	v_pk_fma_f32 v[78:79], v[78:79], v[150:151], v[74:75] op_sel:[0,1,0]
	v_pk_fma_f32 v[150:151], v[92:93], v[150:151], v[88:89] op_sel:[0,1,0]
	v_cvt_pk_f32_fp8_e32 v[92:93], v98
	v_cvt_pk_f32_fp8_sdwa v[88:89], v98 src0_sel:WORD_1
	v_pk_fma_f32 v[92:93], v[92:93], v[152:153], v[84:85] op_sel_hi:[1,0,1]
	v_cvt_pk_f32_fp8_e32 v[84:85], v99
	v_cvt_pk_f32_fp8_sdwa v[98:99], v99 src0_sel:WORD_1
	v_pk_fma_f32 v[88:89], v[88:89], v[152:153], v[154:155] op_sel_hi:[1,0,1]
	v_pk_fma_f32 v[84:85], v[84:85], v[152:153], v[156:157] op_sel_hi:[1,0,1]
	v_pk_fma_f32 v[98:99], v[98:99], v[152:153], v[90:91] op_sel_hi:[1,0,1]
	v_cvt_pk_f32_fp8_e32 v[90:91], v100
	v_pk_fma_f32 v[90:91], v[90:91], v[152:153], v[86:87] op_sel_hi:[1,0,1]
	v_cvt_pk_f32_fp8_sdwa v[86:87], v100 src0_sel:WORD_1
	v_pk_fma_f32 v[86:87], v[86:87], v[152:153], v[82:83] op_sel_hi:[1,0,1]
	v_cvt_pk_f32_fp8_e32 v[82:83], v101
	v_cvt_pk_f32_fp8_sdwa v[100:101], v101 src0_sel:WORD_1
	v_pk_fma_f32 v[82:83], v[82:83], v[152:153], v[78:79] op_sel_hi:[1,0,1]
	v_pk_fma_f32 v[150:151], v[100:101], v[152:153], v[150:151] op_sel_hi:[1,0,1]
	v_cvt_pk_f32_fp8_e32 v[100:101], v102
	v_mov_b32_e32 v152, v153
	v_pk_fma_f32 v[100:101], v[100:101], v[152:153], v[92:93] op_sel_hi:[1,0,1]
	v_cvt_pk_f32_fp8_sdwa v[92:93], v102 src0_sel:WORD_1
	v_pk_fma_f32 v[92:93], v[92:93], v[152:153], v[88:89] op_sel_hi:[1,0,1]
	v_cvt_pk_f32_fp8_e32 v[88:89], v103
	v_cvt_pk_f32_fp8_sdwa v[102:103], v103 src0_sel:WORD_1
	v_pk_fma_f32 v[88:89], v[88:89], v[152:153], v[84:85] op_sel_hi:[1,0,1]
	v_pk_fma_f32 v[102:103], v[102:103], v[152:153], v[98:99] op_sel_hi:[1,0,1]
	v_cvt_pk_f32_fp8_e32 v[98:99], v104
	v_pk_fma_f32 v[98:99], v[98:99], v[152:153], v[90:91] op_sel_hi:[1,0,1]
	v_cvt_pk_f32_fp8_sdwa v[90:91], v104 src0_sel:WORD_1
; __device__ __forceinline__ f32x2 fp8x2_lo(unsigned w) { return __builtin_amdgcn_cvt_pk_f32_fp8(w, false); }
; __device__ __forceinline__ f32x2 fp8x2_hi(unsigned w) { return __builtin_amdgcn_cvt_pk_f32_fp8(w, true); }
; template <bool NT>
; __device__ __forceinline__ void peer_passB(const Args& a, const PeerWork w) {
;     ...
;         for (int k = 0; k < 16; ++k) {
;             const unsigned ww[4] = {vr[k].x, vr[k].y, vr[k].z, vr[k].w};
;             const float c = cf[k >> 2][k & 3]; const f32x2 c2 = {c, c};
; #pragma unroll
;             for (int wd = 0; wd < 4; ++wd) { acc[2 * wd] = __builtin_elementwise_fma(fp8x2_lo(ww[wd]), c2, acc[2 * wd]); acc[2 * wd + 1] = __builtin_elementwise_fma(fp8x2_hi(ww[wd]), c2, acc[2 * wd + 1]); }
;         }
	v_pk_fma_f32 v[90:91], v[90:91], v[152:153], v[86:87] op_sel_hi:[1,0,1]
	v_cvt_pk_f32_fp8_e32 v[86:87], v105
	v_cvt_pk_f32_fp8_sdwa v[104:105], v105 src0_sel:WORD_1
	v_pk_fma_f32 v[86:87], v[86:87], v[152:153], v[82:83] op_sel_hi:[1,0,1]
	v_pk_fma_f32 v[104:105], v[104:105], v[152:153], v[150:151] op_sel_hi:[1,0,1]
	v_cvt_pk_f32_fp8_e32 v[150:151], v106
	v_cvt_pk_f32_fp8_sdwa v[152:153], v106 src0_sel:WORD_1
	v_pk_fma_f32 v[150:151], v[150:151], v[146:147], v[100:101] op_sel_hi:[1,0,1]
	v_cvt_pk_f32_fp8_e32 v[100:101], v107
	v_cvt_pk_f32_fp8_sdwa v[106:107], v107 src0_sel:WORD_1
	v_pk_fma_f32 v[152:153], v[152:153], v[146:147], v[92:93] op_sel_hi:[1,0,1]
	v_pk_fma_f32 v[100:101], v[100:101], v[146:147], v[88:89] op_sel_hi:[1,0,1]
	v_pk_fma_f32 v[106:107], v[106:107], v[146:147], v[102:103] op_sel_hi:[1,0,1]
	v_cvt_pk_f32_fp8_e32 v[102:103], v108
	v_pk_fma_f32 v[102:103], v[102:103], v[146:147], v[98:99] op_sel_hi:[1,0,1]
	v_cvt_pk_f32_fp8_sdwa v[98:99], v108 src0_sel:WORD_1
	v_pk_fma_f32 v[98:99], v[98:99], v[146:147], v[90:91] op_sel_hi:[1,0,1]
	v_cvt_pk_f32_fp8_e32 v[90:91], v109
	v_cvt_pk_f32_fp8_sdwa v[108:109], v109 src0_sel:WORD_1
	v_pk_fma_f32 v[90:91], v[90:91], v[146:147], v[86:87] op_sel_hi:[1,0,1]
	v_pk_fma_f32 v[108:109], v[108:109], v[146:147], v[104:105] op_sel_hi:[1,0,1]
	v_cvt_pk_f32_fp8_e32 v[104:105], v110
	v_pk_fma_f32 v[104:105], v[104:105], v[146:147], v[150:151] op_sel:[0,1,0]
	v_cvt_pk_f32_fp8_sdwa v[150:151], v110 src0_sel:WORD_1
	v_pk_fma_f32 v[150:151], v[150:151], v[146:147], v[152:153] op_sel:[0,1,0]
	v_cvt_pk_f32_fp8_e32 v[152:153], v111
	v_cvt_pk_f32_fp8_sdwa v[110:111], v111 src0_sel:WORD_1
	v_pk_fma_f32 v[152:153], v[152:153], v[146:147], v[100:101] op_sel:[0,1,0]
	v_pk_fma_f32 v[110:111], v[110:111], v[146:147], v[106:107] op_sel:[0,1,0]
	v_cvt_pk_f32_fp8_e32 v[106:107], v112
	v_pk_fma_f32 v[106:107], v[106:107], v[146:147], v[102:103] op_sel:[0,1,0]
	v_cvt_pk_f32_fp8_sdwa v[102:103], v112 src0_sel:WORD_1
	v_pk_fma_f32 v[102:103], v[102:103], v[146:147], v[98:99] op_sel:[0,1,0]
	v_cvt_pk_f32_fp8_e32 v[98:99], v113
	v_cvt_pk_f32_fp8_sdwa v[112:113], v113 src0_sel:WORD_1
	v_pk_fma_f32 v[98:99], v[98:99], v[146:147], v[90:91] op_sel:[0,1,0]
	v_pk_fma_f32 v[146:147], v[112:113], v[146:147], v[108:109] op_sel:[0,1,0]
	v_cvt_pk_f32_fp8_e32 v[112:113], v114
	v_cvt_pk_f32_fp8_sdwa v[108:109], v114 src0_sel:WORD_1
	v_pk_fma_f32 v[112:113], v[112:113], v[148:149], v[104:105] op_sel_hi:[1,0,1]
	v_cvt_pk_f32_fp8_e32 v[104:105], v115
	v_cvt_pk_f32_fp8_sdwa v[114:115], v115 src0_sel:WORD_1
	v_pk_fma_f32 v[108:109], v[108:109], v[148:149], v[150:151] op_sel_hi:[1,0,1]
	v_pk_fma_f32 v[104:105], v[104:105], v[148:149], v[152:153] op_sel_hi:[1,0,1]
	v_pk_fma_f32 v[114:115], v[114:115], v[148:149], v[110:111] op_sel_hi:[1,0,1]
	v_cvt_pk_f32_fp8_e32 v[110:111], v116
	v_pk_fma_f32 v[110:111], v[110:111], v[148:149], v[106:107] op_sel_hi:[1,0,1]
	v_cvt_pk_f32_fp8_sdwa v[106:107], v116 src0_sel:WORD_1
	v_pk_fma_f32 v[106:107], v[106:107], v[148:149], v[102:103] op_sel_hi:[1,0,1]
	v_cvt_pk_f32_fp8_e32 v[102:103], v117
	v_cvt_pk_f32_fp8_sdwa v[116:117], v117 src0_sel:WORD_1
	v_pk_fma_f32 v[102:103], v[102:103], v[148:149], v[98:99] op_sel_hi:[1,0,1]
	v_pk_fma_f32 v[146:147], v[116:117], v[148:149], v[146:147] op_sel_hi:[1,0,1]
	v_cvt_pk_f32_fp8_e32 v[116:117], v118
	v_mov_b32_e32 v148, v149
	v_pk_fma_f32 v[116:117], v[116:117], v[148:149], v[112:113] op_sel_hi:[1,0,1]
	v_cvt_pk_f32_fp8_sdwa v[112:113], v118 src0_sel:WORD_1
	v_pk_fma_f32 v[112:113], v[112:113], v[148:149], v[108:109] op_sel_hi:[1,0,1]
	v_cvt_pk_f32_fp8_e32 v[108:109], v119
	v_cvt_pk_f32_fp8_sdwa v[118:119], v119 src0_sel:WORD_1
	v_pk_fma_f32 v[108:109], v[108:109], v[148:149], v[104:105] op_sel_hi:[1,0,1]
	v_pk_fma_f32 v[118:119], v[118:119], v[148:149], v[114:115] op_sel_hi:[1,0,1]
	v_cvt_pk_f32_fp8_e32 v[114:115], v120
	v_pk_fma_f32 v[114:115], v[114:115], v[148:149], v[110:111] op_sel_hi:[1,0,1]
	v_cvt_pk_f32_fp8_sdwa v[110:111], v120 src0_sel:WORD_1
	v_pk_fma_f32 v[110:111], v[110:111], v[148:149], v[106:107] op_sel_hi:[1,0,1]
	v_cvt_pk_f32_fp8_e32 v[106:107], v121
	v_cvt_pk_f32_fp8_sdwa v[120:121], v121 src0_sel:WORD_1
	v_pk_fma_f32 v[106:107], v[106:107], v[148:149], v[102:103] op_sel_hi:[1,0,1]
	v_pk_fma_f32 v[146:147], v[120:121], v[148:149], v[146:147] op_sel_hi:[1,0,1]
	v_cvt_pk_f32_fp8_e32 v[148:149], v122
	v_cvt_pk_f32_fp8_sdwa v[120:121], v122 src0_sel:WORD_1
	v_pk_fma_f32 v[148:149], v[148:149], v[142:143], v[116:117] op_sel_hi:[1,0,1]
	v_cvt_pk_f32_fp8_e32 v[116:117], v123
	v_cvt_pk_f32_fp8_sdwa v[122:123], v123 src0_sel:WORD_1
	v_pk_fma_f32 v[120:121], v[120:121], v[142:143], v[112:113] op_sel_hi:[1,0,1]
	v_pk_fma_f32 v[116:117], v[116:117], v[142:143], v[108:109] op_sel_hi:[1,0,1]
	v_pk_fma_f32 v[122:123], v[122:123], v[142:143], v[118:119] op_sel_hi:[1,0,1]
	v_cvt_pk_f32_fp8_e32 v[118:119], v124
; template <int CTRL> __device__ __forceinline__ float dpp_f(float x) { return __uint_as_float((unsigned)__builtin_amdgcn_update_dpp(0, (int)__float_as_uint(x), CTRL, 0xf, 0xf, false)); }
; template <bool NT>
; __device__ __forceinline__ void peer_passB(const Args& a, const PeerWork w) {
;     ...
;         float w8[8], w4[4], w2[2];
; #pragma unroll
;         for (int m = 0; m < 8; ++m) { const auto sw = __builtin_amdgcn_permlane32_swap(__float_as_uint(acc[m >> 1][m & 1]), __float_as_uint(acc[(m + 8) >> 1][m & 1]), false, false); w8[m] = __uint_as_float(sw[0]) + __uint_as_float(sw[1]); }
; #pragma unroll
;         for (int m = 0; m < 4; ++m) { const auto sw = __builtin_amdgcn_permlane16_swap(__float_as_uint(w8[m]), __float_as_uint(w8[m + 4]), false, false); w4[m] = __uint_as_float(sw[0]) + __uint_as_float(sw[1]); }
;         { const bool up = (lane & 8) != 0;
; #pragma unroll
;           for (int m = 0; m < 2; ++m) { const float keep = up ? w4[m + 2] : w4[m], send = up ? w4[m] : w4[m + 2]; w2[m] = keep + dpp_f<0x128>(send); } }
;         *(f32x2*)(Y + (size_t)t * DM) = (f32x2){hv[0] + w2[0], hv[1] + w2[1]};
;         if (q + qs > ql) break;
; #pragma unroll
;         for (int k = 0; k < 16; ++k) vr[k] = vrn[k];
; #pragma unroll
;         for (int qq = 0; qq < 4; ++qq) cf[qq] = cfn[qq];
;         hv = hn;
;         t = t1; t1 = t2;
;     }
	v_pk_fma_f32 v[118:119], v[118:119], v[142:143], v[114:115] op_sel_hi:[1,0,1]
	v_cvt_pk_f32_fp8_sdwa v[114:115], v124 src0_sel:WORD_1
	v_pk_fma_f32 v[114:115], v[114:115], v[142:143], v[110:111] op_sel_hi:[1,0,1]
	v_cvt_pk_f32_fp8_e32 v[110:111], v125
	v_cvt_pk_f32_fp8_sdwa v[124:125], v125 src0_sel:WORD_1
	v_pk_fma_f32 v[110:111], v[110:111], v[142:143], v[106:107] op_sel_hi:[1,0,1]
	v_pk_fma_f32 v[124:125], v[124:125], v[142:143], v[146:147] op_sel_hi:[1,0,1]
	v_cvt_pk_f32_fp8_e32 v[146:147], v126
	v_pk_fma_f32 v[146:147], v[146:147], v[142:143], v[148:149] op_sel:[0,1,0]
	v_cvt_pk_f32_fp8_sdwa v[148:149], v126 src0_sel:WORD_1
	v_pk_fma_f32 v[148:149], v[148:149], v[142:143], v[120:121] op_sel:[0,1,0]
	v_cvt_pk_f32_fp8_e32 v[120:121], v127
	v_cvt_pk_f32_fp8_sdwa v[126:127], v127 src0_sel:WORD_1
	v_pk_fma_f32 v[120:121], v[120:121], v[142:143], v[116:117] op_sel:[0,1,0]
	v_pk_fma_f32 v[126:127], v[126:127], v[142:143], v[122:123] op_sel:[0,1,0]
	v_cvt_pk_f32_fp8_e32 v[122:123], v128
	v_pk_fma_f32 v[122:123], v[122:123], v[142:143], v[118:119] op_sel:[0,1,0]
	v_cvt_pk_f32_fp8_sdwa v[118:119], v128 src0_sel:WORD_1
	v_pk_fma_f32 v[118:119], v[118:119], v[142:143], v[114:115] op_sel:[0,1,0]
	v_cvt_pk_f32_fp8_e32 v[114:115], v129
	v_cvt_pk_f32_fp8_sdwa v[128:129], v129 src0_sel:WORD_1
	v_pk_fma_f32 v[114:115], v[114:115], v[142:143], v[110:111] op_sel:[0,1,0]
	v_pk_fma_f32 v[142:143], v[128:129], v[142:143], v[124:125] op_sel:[0,1,0]
	v_cvt_pk_f32_fp8_e32 v[128:129], v130
	v_cvt_pk_f32_fp8_sdwa v[124:125], v130 src0_sel:WORD_1
	v_pk_fma_f32 v[128:129], v[128:129], v[144:145], v[146:147] op_sel_hi:[1,0,1]
	v_cvt_pk_f32_fp8_e32 v[146:147], v131
	v_cvt_pk_f32_fp8_sdwa v[130:131], v131 src0_sel:WORD_1
	v_pk_fma_f32 v[124:125], v[124:125], v[144:145], v[148:149] op_sel_hi:[1,0,1]
	v_cvt_pk_f32_fp8_e32 v[148:149], v133
	v_pk_fma_f32 v[146:147], v[146:147], v[144:145], v[120:121] op_sel_hi:[1,0,1]
	v_pk_fma_f32 v[130:131], v[130:131], v[144:145], v[126:127] op_sel_hi:[1,0,1]
	v_cvt_pk_f32_fp8_e32 v[126:127], v132
	v_pk_fma_f32 v[148:149], v[148:149], v[144:145], v[114:115] op_sel_hi:[1,0,1]
	v_pk_fma_f32 v[126:127], v[126:127], v[144:145], v[122:123] op_sel_hi:[1,0,1]
	v_cvt_pk_f32_fp8_sdwa v[122:123], v132 src0_sel:WORD_1
	v_cvt_pk_f32_fp8_sdwa v[132:133], v133 src0_sel:WORD_1
	v_pk_fma_f32 v[122:123], v[122:123], v[144:145], v[118:119] op_sel_hi:[1,0,1]
	v_pk_fma_f32 v[142:143], v[132:133], v[144:145], v[142:143] op_sel_hi:[1,0,1]
	v_cvt_pk_f32_fp8_e32 v[132:133], v134
	v_mov_b32_e32 v144, v145
	v_pk_fma_f32 v[132:133], v[132:133], v[144:145], v[128:129] op_sel_hi:[1,0,1]
	v_cvt_pk_f32_fp8_sdwa v[128:129], v134 src0_sel:WORD_1
	v_pk_fma_f32 v[128:129], v[128:129], v[144:145], v[124:125] op_sel_hi:[1,0,1]
	v_cvt_pk_f32_fp8_e32 v[124:125], v135
	v_cvt_pk_f32_fp8_sdwa v[134:135], v135 src0_sel:WORD_1
	v_pk_fma_f32 v[124:125], v[124:125], v[144:145], v[146:147] op_sel_hi:[1,0,1]
	v_pk_fma_f32 v[134:135], v[134:135], v[144:145], v[130:131] op_sel_hi:[1,0,1]
	v_cvt_pk_f32_fp8_e32 v[130:131], v136
	v_pk_fma_f32 v[130:131], v[130:131], v[144:145], v[126:127] op_sel_hi:[1,0,1]
	v_cvt_pk_f32_fp8_sdwa v[126:127], v136 src0_sel:WORD_1
	s_nop 0
	v_permlane32_swap_b32_e32 v132, v130
	v_permlane32_swap_b32_e32 v133, v131
	v_pk_fma_f32 v[126:127], v[126:127], v[144:145], v[122:123] op_sel_hi:[1,0,1]
	v_cvt_pk_f32_fp8_e32 v[122:123], v137
	v_cvt_pk_f32_fp8_sdwa v[136:137], v137 src0_sel:WORD_1
	v_permlane32_swap_b32_e32 v128, v126
	v_pk_fma_f32 v[122:123], v[122:123], v[144:145], v[148:149] op_sel_hi:[1,0,1]
	v_pk_fma_f32 v[136:137], v[136:137], v[144:145], v[142:143] op_sel_hi:[1,0,1]
	v_permlane32_swap_b32_e32 v129, v127
	v_permlane32_swap_b32_e32 v124, v122
	v_permlane32_swap_b32_e32 v125, v123
	v_permlane32_swap_b32_e32 v134, v136
	v_permlane32_swap_b32_e32 v135, v137
	v_add_f32_e32 v142, v132, v130
	v_add_f32_e32 v143, v133, v131
	v_add_f32_e32 v144, v128, v126
	v_add_f32_e32 v145, v129, v127
	v_add_f32_e32 v130, v124, v122
	v_add_f32_e32 v131, v125, v123
	v_add_f32_e32 v134, v134, v136
	v_add_f32_e32 v135, v135, v137
	v_permlane16_swap_b32_e32 v142, v130
	v_permlane16_swap_b32_e32 v143, v131
	v_permlane16_swap_b32_e32 v144, v134
	v_permlane16_swap_b32_e32 v145, v135
	v_pk_add_f32 v[136:137], v[142:143], v[130:131]
	v_pk_add_f32 v[134:135], v[144:145], v[134:135]
	v_mov_b32_e32 v142, 0
	v_cndmask_b32_e32 v143, v136, v134, vcc
	v_cndmask_b32_e32 v144, v134, v136, vcc
	v_cndmask_b32_e32 v134, v137, v135, vcc
	v_mov_b32_dpp v142, v143 row_ror:8 row_mask:0xf bank_mask:0xf
	v_mov_b32_e32 v143, 0
	v_cndmask_b32_e32 v145, v135, v137, vcc
	v_lshl_add_u64 v[136:137], v[186:187], 0, s[12:13]
	v_mov_b32_dpp v143, v134 row_ror:8 row_mask:0xf bank_mask:0xf
	v_pk_add_f32 v[134:135], v[144:145], v[142:143]
	v_pk_add_f32 v[134:135], v[188:189], v[134:135]
	global_store_dwordx2 v[136:137], v[134:135], off
	s_mov_b32 s12, s14
	s_cbranch_scc1 .LBB0_1587
	s_waitcnt vmcnt(0)
